# attention phase: static s_setprio 1 for waves 0-3 instead of 4-7 (A/B of the half)
# baseline (speedup 1.0000x reference)
.Lq_pf0:
	s_cmp_ge_u32 s33, 4
	s_cbranch_scc1 .Lprio_skip
	s_setprio 1
